# attention item table re-dealt with skipped-subtile cost 0.55 / 0.25
# baseline (speedup 1.0000x reference)
.Ltbl:
	s_and_b32 s0, s73, 15
	s_mov_b32 s100, 0x402d46b3
	s_cmp_eq_u32 s0, 1
	s_cselect_b32 s100, 0x401cdabc, s100
	s_cmp_eq_u32 s0, 2
	s_cselect_b32 s100, 0x40328c3f, s100
	s_cmp_eq_u32 s0, 3
	s_cselect_b32 s100, 0x402985fd, s100
	s_cmp_eq_u32 s0, 4
	s_cselect_b32 s100, 0x400f9eab, s100
	s_cmp_eq_u32 s0, 5
	s_cselect_b32 s100, 0x4001f72c, s100
	s_cmp_eq_u32 s0, 6
	s_cselect_b32 s100, 0x404194fe, s100
	s_cmp_eq_u32 s0, 7
	s_cselect_b32 s100, 0x403d5e34, s100
	s_cmp_eq_u32 s0, 8
	s_cselect_b32 s100, 0x4005e8af, s100
	s_cmp_eq_u32 s0, 9
	s_cselect_b32 s100, 0x40816925, s100
	s_cmp_eq_u32 s0, 10
	s_cselect_b32 s100, 0x404528e7, s100
	s_cmp_eq_u32 s0, 11
	s_cselect_b32 s100, 0x400a99ad, s100
	s_cmp_eq_u32 s0, 12
	s_cselect_b32 s100, 0x4024ecb6, s100
	s_cmp_eq_u32 s0, 13
	s_cselect_b32 s100, 0x40221775, s100
	s_cmp_eq_u32 s0, 14
	s_cselect_b32 s100, 0x40106bbb, s100
	s_cmp_eq_u32 s0, 15
	s_cselect_b32 s100, 0x401716f7, s100
	s_mov_b32 s74, 0
